# P4a ym_finalize rewritten: 3-slot register ring (2 rows of loads in flight, counted vmcnt), DPP+permlane16 half-wave stats instead of 20 ds_bpermute/row
# baseline (speedup 1.0000x reference)
; #define OPAQUE_TID() int tid = threadIdx.x; asm volatile("" : "+v"(tid)); const int lane = tid & 63, wave = __builtin_amdgcn_readfirstlane(tid >> 6); (void)lane; (void)wave
; #define YM_LOAD(row) do { const bf16_t* ur_ = U + (size_t)(row) * LDU + cbase; _Pragma("unroll") for (int hp = 0; hp < 2; ++hp) { \
;         nh[hp] = *(const u32x4*)(ur_ + C_V + 512 * hp); nz[hp] = *(const u32x4*)(ur_ + C_ZM + 512 * hp); } } while (0)
; __device__ __forceinline__ void ym_finalize(const Args& a, bool dry = false) {
;     OPAQUE_TID();
;     bf16_t* U = (bf16_t*)(a.ws + WS_U);
;     const int gw = blockIdx.x * 8 + wave, NGW = gridDim.x * 8;
;     const int cbase = (lane >> 5) * 256 + 8 * (lane & 31);
;     f32x4 gh[2][2];
; #pragma unroll
;     for (int hp = 0; hp < 2; ++hp) { gh[hp][0] = *(const f32x4*)(a.in[16] + cbase + 512 * hp); gh[hp][1] = *(const f32x4*)(a.in[16] + cbase + 512 * hp + 4); }
;     u32x4 nh[2], nz[2];
;     ...
;     if (gw < MT) YM_LOAD(gw);
;     for (int row = gw; row < MT; row += NGW) {
;         u32x4 ch[2], cz[2];
; #pragma unroll
;         for (int hp = 0; hp < 2; ++hp) { ch[hp] = nh[hp]; cz[hp] = nz[hp]; }
;         if (row + NGW < MT) YM_LOAD(row + NGW);
.LBB0_1128:
	s_or_b64 exec, exec, s[0:1]
	s_bitcmp0_b32 s2, 3
	s_cselect_b64 s[4:5], -1, 0
	s_and_b64 vcc, exec, s[4:5]
	s_waitcnt lgkmcnt(0)
	s_barrier
	s_cbranch_vccnz .LBB0_1134
	v_mov_b32_e32 v20, v180
	v_readlane_b32 s1, v254, 3
	v_readfirstlane_b32 s0, v20
	s_ashr_i32 s0, s0, 6
	s_add_i32 s10, s0, s1
	s_cmp_gt_i32 s10, 0x83ff
	s_cbranch_scc1 .LBB0_1134
	s_mov_b32 s8, s10
	v_and_b32_e32 v67, 63, v180
	v_lshlrev_b32_e32 v66, 5, v67
	v_lshlrev_b32_e32 v64, 4, v67
	v_add_u32_e32 v65, 0x3000, v64
	v_add_u32_e32 v64, 0x1000, v64
	s_mul_i32 s0, s8, 0x3800
	s_mul_hi_i32 s1, s8, 0x3800
	s_add_u32 s0, s28, s0
	s_addc_u32 s1, s29, s1
	s_mul_i32 s9, s34, 0x3800
	s_mul_i32 s10, s34, 2
	s_mul_i32 s99, s9, 2
	s_mov_b32 s98, 0x3b800000
	v_mov_b32_e32 v178, 0x358637bd
	global_load_dwordx4 v[0:3], v66, s[20:21]
	global_load_dwordx4 v[4:7], v66, s[20:21] offset:16
	global_load_dwordx4 v[8:11], v66, s[20:21] offset:2048
	global_load_dwordx4 v[12:15], v66, s[20:21] offset:2064
	s_mov_b32 s6, s0
	s_mov_b32 s7, s1
	global_load_dwordx4 v[16:19], v65, s[6:7]
	global_load_dwordx4 v[20:23], v65, s[6:7] offset:1024
	global_load_dwordx4 v[24:27], v64, s[6:7]
	global_load_dwordx4 v[28:31], v64, s[6:7] offset:1024
	global_load_dword v67, v64, s[0:1]
	global_load_dword v67, v64, s[0:1] offset:1024
	s_add_u32 s6, s6, s9
	s_addc_u32 s7, s7, 0
	global_load_dwordx4 v[32:35], v65, s[6:7]
	global_load_dwordx4 v[36:39], v65, s[6:7] offset:1024
	global_load_dwordx4 v[40:43], v64, s[6:7]
	global_load_dwordx4 v[44:47], v64, s[6:7] offset:1024
	global_load_dword v67, v64, s[0:1]
	global_load_dword v67, v64, s[0:1] offset:1024
.Lym1_loop:
	s_add_i32 s11, s8, s10
	s_cmp_gt_i32 s11, 0x83ff
	s_cbranch_scc1 .Lym1_nopf0
	s_add_u32 s6, s0, s99
	s_addc_u32 s7, s1, 0
	global_load_dwordx4 v[48:51], v65, s[6:7]
	global_load_dwordx4 v[52:55], v65, s[6:7] offset:1024
	global_load_dwordx4 v[56:59], v64, s[6:7]
	global_load_dwordx4 v[60:63], v64, s[6:7] offset:1024
	s_waitcnt vmcnt(12)
	s_branch .Lym1_go0
.Lym1_nopf0:
	s_waitcnt vmcnt(4)
; __device__ __forceinline__ unsigned pk2(float lo, float hi) { unsigned r; asm("v_cvt_pk_bf16_f32 %0, %1, %2" : "=v"(r) : "v"(lo), "v"(hi)); return r; }
; #define YM_LOAD(row) do { const bf16_t* ur_ = U + (size_t)(row) * LDU + cbase; _Pragma("unroll") for (int hp = 0; hp < 2; ++hp) { \
;         nh[hp] = *(const u32x4*)(ur_ + C_V + 512 * hp); nz[hp] = *(const u32x4*)(ur_ + C_ZM + 512 * hp); } } while (0)
; __device__ __forceinline__ void ym_finalize(const Args& a, bool dry = false) {
;     ...
;     for (int row = gw; row < MT; row += NGW) {
;         u32x4 ch[2], cz[2];
; #pragma unroll
;         for (int hp = 0; hp < 2; ++hp) { ch[hp] = nh[hp]; cz[hp] = nz[hp]; }
;         if (row + NGW < MT) YM_LOAD(row + NGW);
; #pragma unroll
;         for (int hp = 0; hp < 2; ++hp) {
;             float x[8], z[8];
;             unpack8(ch[hp], x); unpack8(cz[hp], z);
;             float sm = 0.f;
; #pragma unroll
;             for (int i = 0; i < 8; ++i) sm += x[i];
;             const float mu = half_sum(sm) * (1.f / 256.f);
;             float q = 0.f;
; #pragma unroll
;             for (int i = 0; i < 8; ++i) { x[i] -= mu; q += x[i] * x[i]; }
;             const float rs = rsqrtf(half_sum(q) * (1.f / 256.f) + EPS);
;             float y[8];
; #pragma unroll
;             for (int i = 0; i < 8; ++i) y[i] = x[i] * rs * gh[hp][i >> 2][i & 3] * z[i];
;             bf16_t* dst_ = dry ? (bf16_t*)a.out + (size_t)MT * 1024 + (size_t)row * 1024 + cbase + 512 * hp : U + (size_t)row * LDU + cbase + C_ZM + 512 * hp;
;             *(u32x4*)dst_ = (u32x4){pk2(y[0], y[1]), pk2(y[2], y[3]), pk2(y[4], y[5]), pk2(y[6], y[7])};
;         }
.Lym1_go0:
	v_lshlrev_b32_e32 v100, 16, v16
	v_and_b32_e32 v101, 0xffff0000, v16
	v_lshlrev_b32_e32 v108, 16, v20
	v_and_b32_e32 v109, 0xffff0000, v20
	v_lshlrev_b32_e32 v102, 16, v17
	v_and_b32_e32 v103, 0xffff0000, v17
	v_lshlrev_b32_e32 v110, 16, v21
	v_and_b32_e32 v111, 0xffff0000, v21
	v_lshlrev_b32_e32 v104, 16, v18
	v_and_b32_e32 v105, 0xffff0000, v18
	v_lshlrev_b32_e32 v112, 16, v22
	v_and_b32_e32 v113, 0xffff0000, v22
	v_lshlrev_b32_e32 v106, 16, v19
	v_and_b32_e32 v107, 0xffff0000, v19
	v_lshlrev_b32_e32 v114, 16, v23
	v_and_b32_e32 v115, 0xffff0000, v23
	v_add_f32_e32 v116, v100, v101
	v_add_f32_e32 v117, v108, v109
	v_add_f32_e32 v116, v116, v102
	v_add_f32_e32 v117, v117, v110
	v_add_f32_e32 v116, v116, v103
	v_add_f32_e32 v117, v117, v111
	v_add_f32_e32 v116, v116, v104
	v_add_f32_e32 v117, v117, v112
	v_add_f32_e32 v116, v116, v105
	v_add_f32_e32 v117, v117, v113
	v_add_f32_e32 v116, v116, v106
	v_add_f32_e32 v117, v117, v114
	v_add_f32_e32 v116, v116, v107
	v_add_f32_e32 v117, v117, v115
	s_nop 1
	v_add_f32_dpp v118, v116, v116 quad_perm:[1,0,3,2] row_mask:0xf bank_mask:0xf
	v_add_f32_dpp v119, v117, v117 quad_perm:[1,0,3,2] row_mask:0xf bank_mask:0xf
	s_nop 0
	v_add_f32_dpp v120, v118, v118 quad_perm:[2,3,0,1] row_mask:0xf bank_mask:0xf
	v_add_f32_dpp v121, v119, v119 quad_perm:[2,3,0,1] row_mask:0xf bank_mask:0xf
	s_nop 0
	v_add_f32_dpp v118, v120, v120 row_half_mirror row_mask:0xf bank_mask:0xf
	v_add_f32_dpp v119, v121, v121 row_half_mirror row_mask:0xf bank_mask:0xf
	s_nop 0
	v_add_f32_dpp v120, v118, v118 row_mirror row_mask:0xf bank_mask:0xf
	v_add_f32_dpp v121, v119, v119 row_mirror row_mask:0xf bank_mask:0xf
	v_mov_b32_e32 v118, v120
	v_mov_b32_e32 v119, v121
	s_nop 1
	v_permlane16_swap_b32_e32 v118, v120
	v_permlane16_swap_b32_e32 v119, v121
	s_nop 0
	v_add_f32_e32 v116, v118, v120
	v_add_f32_e32 v117, v119, v121
	v_mul_f32_e32 v116, 0x3b800000, v116
	v_mul_f32_e32 v117, 0x3b800000, v117
	v_sub_f32_e32 v100, v100, v116
	v_sub_f32_e32 v108, v108, v117
	v_sub_f32_e32 v101, v101, v116
	v_sub_f32_e32 v109, v109, v117
	v_sub_f32_e32 v102, v102, v116
	v_sub_f32_e32 v110, v110, v117
	v_sub_f32_e32 v103, v103, v116
	v_sub_f32_e32 v111, v111, v117
	v_sub_f32_e32 v104, v104, v116
	v_sub_f32_e32 v112, v112, v117
	v_sub_f32_e32 v105, v105, v116
	v_sub_f32_e32 v113, v113, v117
	v_sub_f32_e32 v106, v106, v116
	v_sub_f32_e32 v114, v114, v117
	v_sub_f32_e32 v107, v107, v116
	v_sub_f32_e32 v115, v115, v117
	v_mul_f32_e32 v156, v100, v100
	v_mul_f32_e32 v157, v108, v108
	v_fmac_f32_e32 v156, v101, v101
	v_fmac_f32_e32 v157, v109, v109
	v_fmac_f32_e32 v156, v102, v102
	v_fmac_f32_e32 v157, v110, v110
	v_fmac_f32_e32 v156, v103, v103
	v_fmac_f32_e32 v157, v111, v111
	v_fmac_f32_e32 v156, v104, v104
	v_fmac_f32_e32 v157, v112, v112
	v_fmac_f32_e32 v156, v105, v105
	v_fmac_f32_e32 v157, v113, v113
	v_fmac_f32_e32 v156, v106, v106
	v_fmac_f32_e32 v157, v114, v114
	v_fmac_f32_e32 v156, v107, v107
	v_fmac_f32_e32 v157, v115, v115
	s_nop 1
	v_add_f32_dpp v118, v156, v156 quad_perm:[1,0,3,2] row_mask:0xf bank_mask:0xf
	v_add_f32_dpp v119, v157, v157 quad_perm:[1,0,3,2] row_mask:0xf bank_mask:0xf
	s_nop 0
	v_add_f32_dpp v120, v118, v118 quad_perm:[2,3,0,1] row_mask:0xf bank_mask:0xf
	v_add_f32_dpp v121, v119, v119 quad_perm:[2,3,0,1] row_mask:0xf bank_mask:0xf
	s_nop 0
	v_add_f32_dpp v118, v120, v120 row_half_mirror row_mask:0xf bank_mask:0xf
	v_add_f32_dpp v119, v121, v121 row_half_mirror row_mask:0xf bank_mask:0xf
	s_nop 0
	v_add_f32_dpp v120, v118, v118 row_mirror row_mask:0xf bank_mask:0xf
	v_add_f32_dpp v121, v119, v119 row_mirror row_mask:0xf bank_mask:0xf
	v_mov_b32_e32 v118, v120
	v_mov_b32_e32 v119, v121
	s_nop 1
	v_permlane16_swap_b32_e32 v118, v120
	v_permlane16_swap_b32_e32 v119, v121
	s_nop 0
	v_add_f32_e32 v156, v118, v120
	v_add_f32_e32 v157, v119, v121
	v_fma_f32 v156, v156, s98, v178
	v_fma_f32 v157, v157, s98, v178
	v_rsq_f32_e32 v156, v156
	v_rsq_f32_e32 v157, v157
	s_nop 0
	v_lshlrev_b32_e32 v122, 16, v24
	v_and_b32_e32 v123, 0xffff0000, v24
	v_mul_f32_e32 v158, v100, v156
	v_mul_f32_e32 v159, v101, v156
	v_mul_f32_e32 v158, v158, v0
	v_mul_f32_e32 v159, v159, v1
	v_mul_f32_e32 v158, v158, v122
	v_mul_f32_e32 v159, v159, v123
	v_cvt_pk_bf16_f32 v124, v158, v159
	v_lshlrev_b32_e32 v122, 16, v28
	v_and_b32_e32 v123, 0xffff0000, v28
	v_mul_f32_e32 v176, v108, v157
	v_mul_f32_e32 v177, v109, v157
	v_mul_f32_e32 v176, v176, v8
	v_mul_f32_e32 v177, v177, v9
	v_mul_f32_e32 v176, v176, v122
	v_mul_f32_e32 v177, v177, v123
	v_cvt_pk_bf16_f32 v152, v176, v177
	v_lshlrev_b32_e32 v122, 16, v25
	v_and_b32_e32 v123, 0xffff0000, v25
	v_mul_f32_e32 v158, v102, v156
	v_mul_f32_e32 v159, v103, v156
	v_mul_f32_e32 v158, v158, v2
	v_mul_f32_e32 v159, v159, v3
	v_mul_f32_e32 v158, v158, v122
	v_mul_f32_e32 v159, v159, v123
	v_cvt_pk_bf16_f32 v125, v158, v159
	v_lshlrev_b32_e32 v122, 16, v29
	v_and_b32_e32 v123, 0xffff0000, v29
	v_mul_f32_e32 v176, v110, v157
	v_mul_f32_e32 v177, v111, v157
	v_mul_f32_e32 v176, v176, v10
	v_mul_f32_e32 v177, v177, v11
	v_mul_f32_e32 v176, v176, v122
	v_mul_f32_e32 v177, v177, v123
	v_cvt_pk_bf16_f32 v153, v176, v177
	v_lshlrev_b32_e32 v122, 16, v26
	v_and_b32_e32 v123, 0xffff0000, v26
	v_mul_f32_e32 v158, v104, v156
	v_mul_f32_e32 v159, v105, v156
	v_mul_f32_e32 v158, v158, v4
	v_mul_f32_e32 v159, v159, v5
	v_mul_f32_e32 v158, v158, v122
	v_mul_f32_e32 v159, v159, v123
	v_cvt_pk_bf16_f32 v126, v158, v159
	v_lshlrev_b32_e32 v122, 16, v30
	v_and_b32_e32 v123, 0xffff0000, v30
	v_mul_f32_e32 v176, v112, v157
	v_mul_f32_e32 v177, v113, v157
	v_mul_f32_e32 v176, v176, v12
	v_mul_f32_e32 v177, v177, v13
	v_mul_f32_e32 v176, v176, v122
	v_mul_f32_e32 v177, v177, v123
	v_cvt_pk_bf16_f32 v154, v176, v177
	v_lshlrev_b32_e32 v122, 16, v27
	v_and_b32_e32 v123, 0xffff0000, v27
	v_mul_f32_e32 v158, v106, v156
	v_mul_f32_e32 v159, v107, v156
	v_mul_f32_e32 v158, v158, v6
	v_mul_f32_e32 v159, v159, v7
	v_mul_f32_e32 v158, v158, v122
	v_mul_f32_e32 v159, v159, v123
	v_cvt_pk_bf16_f32 v127, v158, v159
	v_lshlrev_b32_e32 v122, 16, v31
	v_and_b32_e32 v123, 0xffff0000, v31
	v_mul_f32_e32 v176, v114, v157
	v_mul_f32_e32 v177, v115, v157
	v_mul_f32_e32 v176, v176, v14
	v_mul_f32_e32 v177, v177, v15
	v_mul_f32_e32 v176, v176, v122
	v_mul_f32_e32 v177, v177, v123
	v_cvt_pk_bf16_f32 v155, v176, v177
	global_store_dwordx4 v64, v[124:127], s[0:1]
	global_store_dwordx4 v64, v[152:155], s[0:1] offset:1024
	s_add_i32 s8, s8, s34
	s_add_u32 s0, s0, s9
	s_addc_u32 s1, s1, 0
	s_cmp_gt_i32 s8, 0x83ff
	s_cbranch_scc1 .LBB0_1134
	s_add_i32 s11, s8, s10
	s_cmp_gt_i32 s11, 0x83ff
	s_cbranch_scc1 .Lym1_nopf1
	s_add_u32 s6, s0, s99
	s_addc_u32 s7, s1, 0
	global_load_dwordx4 v[16:19], v65, s[6:7]
	global_load_dwordx4 v[20:23], v65, s[6:7] offset:1024
	global_load_dwordx4 v[24:27], v64, s[6:7]
	global_load_dwordx4 v[28:31], v64, s[6:7] offset:1024
	s_waitcnt vmcnt(12)
	s_branch .Lym1_go1

; __device__ __forceinline__ unsigned pk2(float lo, float hi) { unsigned r; asm("v_cvt_pk_bf16_f32 %0, %1, %2" : "=v"(r) : "v"(lo), "v"(hi)); return r; }
; #define YM_LOAD(row) do { const bf16_t* ur_ = U + (size_t)(row) * LDU + cbase; _Pragma("unroll") for (int hp = 0; hp < 2; ++hp) { \
;         nh[hp] = *(const u32x4*)(ur_ + C_V + 512 * hp); nz[hp] = *(const u32x4*)(ur_ + C_ZM + 512 * hp); } } while (0)
; __device__ __forceinline__ void ym_finalize(const Args& a, bool dry = false) {
;     ...
;     for (int row = gw; row < MT; row += NGW) {
;         u32x4 ch[2], cz[2];
; #pragma unroll
;         for (int hp = 0; hp < 2; ++hp) { ch[hp] = nh[hp]; cz[hp] = nz[hp]; }
;         if (row + NGW < MT) YM_LOAD(row + NGW);
; #pragma unroll
;         for (int hp = 0; hp < 2; ++hp) {
;             float x[8], z[8];
;             unpack8(ch[hp], x); unpack8(cz[hp], z);
;             float sm = 0.f;
; #pragma unroll
;             for (int i = 0; i < 8; ++i) sm += x[i];
;             const float mu = half_sum(sm) * (1.f / 256.f);
;             float q = 0.f;
; #pragma unroll
;             for (int i = 0; i < 8; ++i) { x[i] -= mu; q += x[i] * x[i]; }
;             const float rs = rsqrtf(half_sum(q) * (1.f / 256.f) + EPS);
;             float y[8];
; #pragma unroll
;             for (int i = 0; i < 8; ++i) y[i] = x[i] * rs * gh[hp][i >> 2][i & 3] * z[i];
;             bf16_t* dst_ = dry ? (bf16_t*)a.out + (size_t)MT * 1024 + (size_t)row * 1024 + cbase + 512 * hp : U + (size_t)row * LDU + cbase + C_ZM + 512 * hp;
;             *(u32x4*)dst_ = (u32x4){pk2(y[0], y[1]), pk2(y[2], y[3]), pk2(y[4], y[5]), pk2(y[6], y[7])};
;         }
.Lym1_go1:
	v_lshlrev_b32_e32 v100, 16, v32
	v_and_b32_e32 v101, 0xffff0000, v32
	v_lshlrev_b32_e32 v108, 16, v36
	v_and_b32_e32 v109, 0xffff0000, v36
	v_lshlrev_b32_e32 v102, 16, v33
	v_and_b32_e32 v103, 0xffff0000, v33
	v_lshlrev_b32_e32 v110, 16, v37
	v_and_b32_e32 v111, 0xffff0000, v37
	v_lshlrev_b32_e32 v104, 16, v34
	v_and_b32_e32 v105, 0xffff0000, v34
	v_lshlrev_b32_e32 v112, 16, v38
	v_and_b32_e32 v113, 0xffff0000, v38
	v_lshlrev_b32_e32 v106, 16, v35
	v_and_b32_e32 v107, 0xffff0000, v35
	v_lshlrev_b32_e32 v114, 16, v39
	v_and_b32_e32 v115, 0xffff0000, v39
	v_add_f32_e32 v116, v100, v101
	v_add_f32_e32 v117, v108, v109
	v_add_f32_e32 v116, v116, v102
	v_add_f32_e32 v117, v117, v110
	v_add_f32_e32 v116, v116, v103
	v_add_f32_e32 v117, v117, v111
	v_add_f32_e32 v116, v116, v104
	v_add_f32_e32 v117, v117, v112
	v_add_f32_e32 v116, v116, v105
	v_add_f32_e32 v117, v117, v113
	v_add_f32_e32 v116, v116, v106
	v_add_f32_e32 v117, v117, v114
	v_add_f32_e32 v116, v116, v107
	v_add_f32_e32 v117, v117, v115
	s_nop 1
	v_add_f32_dpp v118, v116, v116 quad_perm:[1,0,3,2] row_mask:0xf bank_mask:0xf
	v_add_f32_dpp v119, v117, v117 quad_perm:[1,0,3,2] row_mask:0xf bank_mask:0xf
	s_nop 0
	v_add_f32_dpp v120, v118, v118 quad_perm:[2,3,0,1] row_mask:0xf bank_mask:0xf
	v_add_f32_dpp v121, v119, v119 quad_perm:[2,3,0,1] row_mask:0xf bank_mask:0xf
	s_nop 0
	v_add_f32_dpp v118, v120, v120 row_half_mirror row_mask:0xf bank_mask:0xf
	v_add_f32_dpp v119, v121, v121 row_half_mirror row_mask:0xf bank_mask:0xf
	s_nop 0
	v_add_f32_dpp v120, v118, v118 row_mirror row_mask:0xf bank_mask:0xf
	v_add_f32_dpp v121, v119, v119 row_mirror row_mask:0xf bank_mask:0xf
	v_mov_b32_e32 v118, v120
	v_mov_b32_e32 v119, v121
	s_nop 1
	v_permlane16_swap_b32_e32 v118, v120
	v_permlane16_swap_b32_e32 v119, v121
	s_nop 0
	v_add_f32_e32 v116, v118, v120
	v_add_f32_e32 v117, v119, v121
	v_mul_f32_e32 v116, 0x3b800000, v116
	v_mul_f32_e32 v117, 0x3b800000, v117
	v_sub_f32_e32 v100, v100, v116
	v_sub_f32_e32 v108, v108, v117
	v_sub_f32_e32 v101, v101, v116
	v_sub_f32_e32 v109, v109, v117
	v_sub_f32_e32 v102, v102, v116
	v_sub_f32_e32 v110, v110, v117
	v_sub_f32_e32 v103, v103, v116
	v_sub_f32_e32 v111, v111, v117
	v_sub_f32_e32 v104, v104, v116
	v_sub_f32_e32 v112, v112, v117
	v_sub_f32_e32 v105, v105, v116
	v_sub_f32_e32 v113, v113, v117
	v_sub_f32_e32 v106, v106, v116
	v_sub_f32_e32 v114, v114, v117
	v_sub_f32_e32 v107, v107, v116
	v_sub_f32_e32 v115, v115, v117
	v_mul_f32_e32 v156, v100, v100
	v_mul_f32_e32 v157, v108, v108
	v_fmac_f32_e32 v156, v101, v101
	v_fmac_f32_e32 v157, v109, v109
	v_fmac_f32_e32 v156, v102, v102
	v_fmac_f32_e32 v157, v110, v110
	v_fmac_f32_e32 v156, v103, v103
	v_fmac_f32_e32 v157, v111, v111
	v_fmac_f32_e32 v156, v104, v104
	v_fmac_f32_e32 v157, v112, v112
	v_fmac_f32_e32 v156, v105, v105
	v_fmac_f32_e32 v157, v113, v113
	v_fmac_f32_e32 v156, v106, v106
	v_fmac_f32_e32 v157, v114, v114
	v_fmac_f32_e32 v156, v107, v107
	v_fmac_f32_e32 v157, v115, v115
	s_nop 1
	v_add_f32_dpp v118, v156, v156 quad_perm:[1,0,3,2] row_mask:0xf bank_mask:0xf
	v_add_f32_dpp v119, v157, v157 quad_perm:[1,0,3,2] row_mask:0xf bank_mask:0xf
	s_nop 0
	v_add_f32_dpp v120, v118, v118 quad_perm:[2,3,0,1] row_mask:0xf bank_mask:0xf
	v_add_f32_dpp v121, v119, v119 quad_perm:[2,3,0,1] row_mask:0xf bank_mask:0xf
	s_nop 0
	v_add_f32_dpp v118, v120, v120 row_half_mirror row_mask:0xf bank_mask:0xf
	v_add_f32_dpp v119, v121, v121 row_half_mirror row_mask:0xf bank_mask:0xf
	s_nop 0
	v_add_f32_dpp v120, v118, v118 row_mirror row_mask:0xf bank_mask:0xf
	v_add_f32_dpp v121, v119, v119 row_mirror row_mask:0xf bank_mask:0xf
	v_mov_b32_e32 v118, v120
	v_mov_b32_e32 v119, v121
	s_nop 1
	v_permlane16_swap_b32_e32 v118, v120
	v_permlane16_swap_b32_e32 v119, v121
	s_nop 0
	v_add_f32_e32 v156, v118, v120
	v_add_f32_e32 v157, v119, v121
	v_fma_f32 v156, v156, s98, v178
	v_fma_f32 v157, v157, s98, v178
	v_rsq_f32_e32 v156, v156
	v_rsq_f32_e32 v157, v157
	s_nop 0
	v_lshlrev_b32_e32 v122, 16, v40
	v_and_b32_e32 v123, 0xffff0000, v40
	v_mul_f32_e32 v158, v100, v156
	v_mul_f32_e32 v159, v101, v156
	v_mul_f32_e32 v158, v158, v0
	v_mul_f32_e32 v159, v159, v1
	v_mul_f32_e32 v158, v158, v122
	v_mul_f32_e32 v159, v159, v123
	v_cvt_pk_bf16_f32 v124, v158, v159
	v_lshlrev_b32_e32 v122, 16, v44
	v_and_b32_e32 v123, 0xffff0000, v44
	v_mul_f32_e32 v176, v108, v157
	v_mul_f32_e32 v177, v109, v157
	v_mul_f32_e32 v176, v176, v8
	v_mul_f32_e32 v177, v177, v9
	v_mul_f32_e32 v176, v176, v122
	v_mul_f32_e32 v177, v177, v123
	v_cvt_pk_bf16_f32 v152, v176, v177
	v_lshlrev_b32_e32 v122, 16, v41
	v_and_b32_e32 v123, 0xffff0000, v41
	v_mul_f32_e32 v158, v102, v156
	v_mul_f32_e32 v159, v103, v156
	v_mul_f32_e32 v158, v158, v2
	v_mul_f32_e32 v159, v159, v3
	v_mul_f32_e32 v158, v158, v122
	v_mul_f32_e32 v159, v159, v123
	v_cvt_pk_bf16_f32 v125, v158, v159
	v_lshlrev_b32_e32 v122, 16, v45
	v_and_b32_e32 v123, 0xffff0000, v45
	v_mul_f32_e32 v176, v110, v157
	v_mul_f32_e32 v177, v111, v157
	v_mul_f32_e32 v176, v176, v10
	v_mul_f32_e32 v177, v177, v11
	v_mul_f32_e32 v176, v176, v122
	v_mul_f32_e32 v177, v177, v123
	v_cvt_pk_bf16_f32 v153, v176, v177
	v_lshlrev_b32_e32 v122, 16, v42
	v_and_b32_e32 v123, 0xffff0000, v42
	v_mul_f32_e32 v158, v104, v156
	v_mul_f32_e32 v159, v105, v156
	v_mul_f32_e32 v158, v158, v4
	v_mul_f32_e32 v159, v159, v5
	v_mul_f32_e32 v158, v158, v122
	v_mul_f32_e32 v159, v159, v123
	v_cvt_pk_bf16_f32 v126, v158, v159
	v_lshlrev_b32_e32 v122, 16, v46
	v_and_b32_e32 v123, 0xffff0000, v46
	v_mul_f32_e32 v176, v112, v157
	v_mul_f32_e32 v177, v113, v157
	v_mul_f32_e32 v176, v176, v12
	v_mul_f32_e32 v177, v177, v13
	v_mul_f32_e32 v176, v176, v122
	v_mul_f32_e32 v177, v177, v123
	v_cvt_pk_bf16_f32 v154, v176, v177
	v_lshlrev_b32_e32 v122, 16, v43
	v_and_b32_e32 v123, 0xffff0000, v43
	v_mul_f32_e32 v158, v106, v156
	v_mul_f32_e32 v159, v107, v156
	v_mul_f32_e32 v158, v158, v6
	v_mul_f32_e32 v159, v159, v7
	v_mul_f32_e32 v158, v158, v122
	v_mul_f32_e32 v159, v159, v123
	v_cvt_pk_bf16_f32 v127, v158, v159
	v_lshlrev_b32_e32 v122, 16, v47
	v_and_b32_e32 v123, 0xffff0000, v47
	v_mul_f32_e32 v176, v114, v157
	v_mul_f32_e32 v177, v115, v157
	v_mul_f32_e32 v176, v176, v14
	v_mul_f32_e32 v177, v177, v15
	v_mul_f32_e32 v176, v176, v122
	v_mul_f32_e32 v177, v177, v123
	v_cvt_pk_bf16_f32 v155, v176, v177
	global_store_dwordx4 v64, v[124:127], s[0:1]
	global_store_dwordx4 v64, v[152:155], s[0:1] offset:1024
	s_add_i32 s8, s8, s34
	s_add_u32 s0, s0, s9
	s_addc_u32 s1, s1, 0
	s_cmp_gt_i32 s8, 0x83ff
	s_cbranch_scc1 .LBB0_1134
	s_add_i32 s11, s8, s10
	s_cmp_gt_i32 s11, 0x83ff
	s_cbranch_scc1 .Lym1_nopf2
	s_add_u32 s6, s0, s99
	s_addc_u32 s7, s1, 0
	global_load_dwordx4 v[32:35], v65, s[6:7]
	global_load_dwordx4 v[36:39], v65, s[6:7] offset:1024
	global_load_dwordx4 v[40:43], v64, s[6:7]
	global_load_dwordx4 v[44:47], v64, s[6:7] offset:1024
	s_waitcnt vmcnt(12)
	s_branch .Lym1_go2

; __device__ __forceinline__ unsigned pk2(float lo, float hi) { unsigned r; asm("v_cvt_pk_bf16_f32 %0, %1, %2" : "=v"(r) : "v"(lo), "v"(hi)); return r; }
; #define YM_LOAD(row) do { const bf16_t* ur_ = U + (size_t)(row) * LDU + cbase; _Pragma("unroll") for (int hp = 0; hp < 2; ++hp) { \
;         nh[hp] = *(const u32x4*)(ur_ + C_V + 512 * hp); nz[hp] = *(const u32x4*)(ur_ + C_ZM + 512 * hp); } } while (0)
; __device__ __forceinline__ void ym_finalize(const Args& a, bool dry = false) {
;     ...
;     for (int row = gw; row < MT; row += NGW) {
;         u32x4 ch[2], cz[2];
; #pragma unroll
;         for (int hp = 0; hp < 2; ++hp) { ch[hp] = nh[hp]; cz[hp] = nz[hp]; }
;         if (row + NGW < MT) YM_LOAD(row + NGW);
; #pragma unroll
;         for (int hp = 0; hp < 2; ++hp) {
;             float x[8], z[8];
;             unpack8(ch[hp], x); unpack8(cz[hp], z);
;             float sm = 0.f;
; #pragma unroll
;             for (int i = 0; i < 8; ++i) sm += x[i];
;             const float mu = half_sum(sm) * (1.f / 256.f);
;             float q = 0.f;
; #pragma unroll
;             for (int i = 0; i < 8; ++i) { x[i] -= mu; q += x[i] * x[i]; }
;             const float rs = rsqrtf(half_sum(q) * (1.f / 256.f) + EPS);
;             float y[8];
; #pragma unroll
;             for (int i = 0; i < 8; ++i) y[i] = x[i] * rs * gh[hp][i >> 2][i & 3] * z[i];
;             bf16_t* dst_ = dry ? (bf16_t*)a.out + (size_t)MT * 1024 + (size_t)row * 1024 + cbase + 512 * hp : U + (size_t)row * LDU + cbase + C_ZM + 512 * hp;
;             *(u32x4*)dst_ = (u32x4){pk2(y[0], y[1]), pk2(y[2], y[3]), pk2(y[4], y[5]), pk2(y[6], y[7])};
;         }
.Lym1_go2:
	v_lshlrev_b32_e32 v100, 16, v48
	v_and_b32_e32 v101, 0xffff0000, v48
	v_lshlrev_b32_e32 v108, 16, v52
	v_and_b32_e32 v109, 0xffff0000, v52
	v_lshlrev_b32_e32 v102, 16, v49
	v_and_b32_e32 v103, 0xffff0000, v49
	v_lshlrev_b32_e32 v110, 16, v53
	v_and_b32_e32 v111, 0xffff0000, v53
	v_lshlrev_b32_e32 v104, 16, v50
	v_and_b32_e32 v105, 0xffff0000, v50
	v_lshlrev_b32_e32 v112, 16, v54
	v_and_b32_e32 v113, 0xffff0000, v54
	v_lshlrev_b32_e32 v106, 16, v51
	v_and_b32_e32 v107, 0xffff0000, v51
	v_lshlrev_b32_e32 v114, 16, v55
	v_and_b32_e32 v115, 0xffff0000, v55
	v_add_f32_e32 v116, v100, v101
	v_add_f32_e32 v117, v108, v109
	v_add_f32_e32 v116, v116, v102
	v_add_f32_e32 v117, v117, v110
	v_add_f32_e32 v116, v116, v103
	v_add_f32_e32 v117, v117, v111
	v_add_f32_e32 v116, v116, v104
	v_add_f32_e32 v117, v117, v112
	v_add_f32_e32 v116, v116, v105
	v_add_f32_e32 v117, v117, v113
	v_add_f32_e32 v116, v116, v106
	v_add_f32_e32 v117, v117, v114
	v_add_f32_e32 v116, v116, v107
	v_add_f32_e32 v117, v117, v115
	s_nop 1
	v_add_f32_dpp v118, v116, v116 quad_perm:[1,0,3,2] row_mask:0xf bank_mask:0xf
	v_add_f32_dpp v119, v117, v117 quad_perm:[1,0,3,2] row_mask:0xf bank_mask:0xf
	s_nop 0
	v_add_f32_dpp v120, v118, v118 quad_perm:[2,3,0,1] row_mask:0xf bank_mask:0xf
	v_add_f32_dpp v121, v119, v119 quad_perm:[2,3,0,1] row_mask:0xf bank_mask:0xf
	s_nop 0
	v_add_f32_dpp v118, v120, v120 row_half_mirror row_mask:0xf bank_mask:0xf
	v_add_f32_dpp v119, v121, v121 row_half_mirror row_mask:0xf bank_mask:0xf
	s_nop 0
	v_add_f32_dpp v120, v118, v118 row_mirror row_mask:0xf bank_mask:0xf
	v_add_f32_dpp v121, v119, v119 row_mirror row_mask:0xf bank_mask:0xf
	v_mov_b32_e32 v118, v120
	v_mov_b32_e32 v119, v121
	s_nop 1
	v_permlane16_swap_b32_e32 v118, v120
	v_permlane16_swap_b32_e32 v119, v121
	s_nop 0
	v_add_f32_e32 v116, v118, v120
	v_add_f32_e32 v117, v119, v121
	v_mul_f32_e32 v116, 0x3b800000, v116
	v_mul_f32_e32 v117, 0x3b800000, v117
	v_sub_f32_e32 v100, v100, v116
	v_sub_f32_e32 v108, v108, v117
	v_sub_f32_e32 v101, v101, v116
	v_sub_f32_e32 v109, v109, v117
	v_sub_f32_e32 v102, v102, v116
	v_sub_f32_e32 v110, v110, v117
	v_sub_f32_e32 v103, v103, v116
	v_sub_f32_e32 v111, v111, v117
	v_sub_f32_e32 v104, v104, v116
	v_sub_f32_e32 v112, v112, v117
	v_sub_f32_e32 v105, v105, v116
	v_sub_f32_e32 v113, v113, v117
	v_sub_f32_e32 v106, v106, v116
	v_sub_f32_e32 v114, v114, v117
	v_sub_f32_e32 v107, v107, v116
	v_sub_f32_e32 v115, v115, v117
	v_mul_f32_e32 v156, v100, v100
	v_mul_f32_e32 v157, v108, v108
	v_fmac_f32_e32 v156, v101, v101
	v_fmac_f32_e32 v157, v109, v109
	v_fmac_f32_e32 v156, v102, v102
	v_fmac_f32_e32 v157, v110, v110
	v_fmac_f32_e32 v156, v103, v103
	v_fmac_f32_e32 v157, v111, v111
	v_fmac_f32_e32 v156, v104, v104
	v_fmac_f32_e32 v157, v112, v112
	v_fmac_f32_e32 v156, v105, v105
	v_fmac_f32_e32 v157, v113, v113
	v_fmac_f32_e32 v156, v106, v106
	v_fmac_f32_e32 v157, v114, v114
	v_fmac_f32_e32 v156, v107, v107
	v_fmac_f32_e32 v157, v115, v115
	s_nop 1
	v_add_f32_dpp v118, v156, v156 quad_perm:[1,0,3,2] row_mask:0xf bank_mask:0xf
	v_add_f32_dpp v119, v157, v157 quad_perm:[1,0,3,2] row_mask:0xf bank_mask:0xf
	s_nop 0
	v_add_f32_dpp v120, v118, v118 quad_perm:[2,3,0,1] row_mask:0xf bank_mask:0xf
	v_add_f32_dpp v121, v119, v119 quad_perm:[2,3,0,1] row_mask:0xf bank_mask:0xf
	s_nop 0
	v_add_f32_dpp v118, v120, v120 row_half_mirror row_mask:0xf bank_mask:0xf
	v_add_f32_dpp v119, v121, v121 row_half_mirror row_mask:0xf bank_mask:0xf
	s_nop 0
	v_add_f32_dpp v120, v118, v118 row_mirror row_mask:0xf bank_mask:0xf
	v_add_f32_dpp v121, v119, v119 row_mirror row_mask:0xf bank_mask:0xf
	v_mov_b32_e32 v118, v120
	v_mov_b32_e32 v119, v121
	s_nop 1
	v_permlane16_swap_b32_e32 v118, v120
	v_permlane16_swap_b32_e32 v119, v121
	s_nop 0
	v_add_f32_e32 v156, v118, v120
	v_add_f32_e32 v157, v119, v121
	v_fma_f32 v156, v156, s98, v178
	v_fma_f32 v157, v157, s98, v178
	v_rsq_f32_e32 v156, v156
	v_rsq_f32_e32 v157, v157
	s_nop 0
	v_lshlrev_b32_e32 v122, 16, v56
	v_and_b32_e32 v123, 0xffff0000, v56
	v_mul_f32_e32 v158, v100, v156
	v_mul_f32_e32 v159, v101, v156
	v_mul_f32_e32 v158, v158, v0
	v_mul_f32_e32 v159, v159, v1
	v_mul_f32_e32 v158, v158, v122
	v_mul_f32_e32 v159, v159, v123
	v_cvt_pk_bf16_f32 v124, v158, v159
	v_lshlrev_b32_e32 v122, 16, v60
	v_and_b32_e32 v123, 0xffff0000, v60
	v_mul_f32_e32 v176, v108, v157
	v_mul_f32_e32 v177, v109, v157
	v_mul_f32_e32 v176, v176, v8
	v_mul_f32_e32 v177, v177, v9
	v_mul_f32_e32 v176, v176, v122
	v_mul_f32_e32 v177, v177, v123
	v_cvt_pk_bf16_f32 v152, v176, v177
	v_lshlrev_b32_e32 v122, 16, v57
	v_and_b32_e32 v123, 0xffff0000, v57
	v_mul_f32_e32 v158, v102, v156
	v_mul_f32_e32 v159, v103, v156
	v_mul_f32_e32 v158, v158, v2
	v_mul_f32_e32 v159, v159, v3
	v_mul_f32_e32 v158, v158, v122
	v_mul_f32_e32 v159, v159, v123
	v_cvt_pk_bf16_f32 v125, v158, v159
	v_lshlrev_b32_e32 v122, 16, v61
	v_and_b32_e32 v123, 0xffff0000, v61
	v_mul_f32_e32 v176, v110, v157
	v_mul_f32_e32 v177, v111, v157
	v_mul_f32_e32 v176, v176, v10
	v_mul_f32_e32 v177, v177, v11
	v_mul_f32_e32 v176, v176, v122
	v_mul_f32_e32 v177, v177, v123
	v_cvt_pk_bf16_f32 v153, v176, v177
	v_lshlrev_b32_e32 v122, 16, v58
	v_and_b32_e32 v123, 0xffff0000, v58
	v_mul_f32_e32 v158, v104, v156
	v_mul_f32_e32 v159, v105, v156
	v_mul_f32_e32 v158, v158, v4
	v_mul_f32_e32 v159, v159, v5
	v_mul_f32_e32 v158, v158, v122
	v_mul_f32_e32 v159, v159, v123
	v_cvt_pk_bf16_f32 v126, v158, v159
	v_lshlrev_b32_e32 v122, 16, v62
	v_and_b32_e32 v123, 0xffff0000, v62
	v_mul_f32_e32 v176, v112, v157
	v_mul_f32_e32 v177, v113, v157
	v_mul_f32_e32 v176, v176, v12
	v_mul_f32_e32 v177, v177, v13
	v_mul_f32_e32 v176, v176, v122
	v_mul_f32_e32 v177, v177, v123
	v_cvt_pk_bf16_f32 v154, v176, v177
	v_lshlrev_b32_e32 v122, 16, v59
	v_and_b32_e32 v123, 0xffff0000, v59
	v_mul_f32_e32 v158, v106, v156
	v_mul_f32_e32 v159, v107, v156
	v_mul_f32_e32 v158, v158, v6
	v_mul_f32_e32 v159, v159, v7
	v_mul_f32_e32 v158, v158, v122
	v_mul_f32_e32 v159, v159, v123
	v_cvt_pk_bf16_f32 v127, v158, v159
	v_lshlrev_b32_e32 v122, 16, v63
	v_and_b32_e32 v123, 0xffff0000, v63
	v_mul_f32_e32 v176, v114, v157
	v_mul_f32_e32 v177, v115, v157
	v_mul_f32_e32 v176, v176, v14
	v_mul_f32_e32 v177, v177, v15
	v_mul_f32_e32 v176, v176, v122
	v_mul_f32_e32 v177, v177, v123
	v_cvt_pk_bf16_f32 v155, v176, v177
	global_store_dwordx4 v64, v[124:127], s[0:1]
	global_store_dwordx4 v64, v[152:155], s[0:1] offset:1024
	s_add_i32 s8, s8, s34
	s_add_u32 s0, s0, s9
	s_addc_u32 s1, s1, 0
	s_cmp_gt_i32 s8, 0x83ff
	s_cbranch_scc0 .Lym1_loop

; #define OPAQUE_TID() int tid = threadIdx.x; asm volatile("" : "+v"(tid)); const int lane = tid & 63, wave = __builtin_amdgcn_readfirstlane(tid >> 6); (void)lane; (void)wave
; #define YM_LOAD(row) do { const bf16_t* ur_ = U + (size_t)(row) * LDU + cbase; _Pragma("unroll") for (int hp = 0; hp < 2; ++hp) { \
;         nh[hp] = *(const u32x4*)(ur_ + C_V + 512 * hp); nz[hp] = *(const u32x4*)(ur_ + C_ZM + 512 * hp); } } while (0)
; __device__ __forceinline__ void ym_finalize(const Args& a, bool dry = false) {
;     OPAQUE_TID();
;     bf16_t* U = (bf16_t*)(a.ws + WS_U);
;     const int gw = blockIdx.x * 8 + wave, NGW = gridDim.x * 8;
;     const int cbase = (lane >> 5) * 256 + 8 * (lane & 31);
;     f32x4 gh[2][2];
; #pragma unroll
;     for (int hp = 0; hp < 2; ++hp) { gh[hp][0] = *(const f32x4*)(a.in[16] + cbase + 512 * hp); gh[hp][1] = *(const f32x4*)(a.in[16] + cbase + 512 * hp + 4); }
;     u32x4 nh[2], nz[2];
;     ...
;     if (gw < MT) YM_LOAD(gw);
;     for (int row = gw; row < MT; row += NGW) {
;         u32x4 ch[2], cz[2];
; #pragma unroll
;         for (int hp = 0; hp < 2; ++hp) { ch[hp] = nh[hp]; cz[hp] = nz[hp]; }
;         if (row + NGW < MT) YM_LOAD(row + NGW);
; __global__ void __launch_bounds__(512, 2) fwd_megakernel(Args a) {
;     ...
;         if (!((bid >> 3) & 1)) ym_finalize(a);
.LBB0_1148:
	s_andn2_b64 vcc, exec, s[4:5]
	s_cbranch_vccnz .LBB0_1154
	v_mov_b32_e32 v20, v180
	v_readlane_b32 s1, v254, 3
	v_readfirstlane_b32 s0, v20
	s_ashr_i32 s0, s0, 6
	s_add_i32 s8, s0, s1
	s_cmp_gt_i32 s8, 0x83ff
	s_cbranch_scc1 .LBB0_1154
	v_and_b32_e32 v67, 63, v180
	v_lshlrev_b32_e32 v66, 5, v67
	v_lshlrev_b32_e32 v64, 4, v67
	v_add_u32_e32 v65, 0x3000, v64
	v_add_u32_e32 v64, 0x1000, v64
	s_mul_i32 s0, s8, 0x3800
	s_mul_hi_i32 s1, s8, 0x3800
	s_add_u32 s0, s28, s0
	s_addc_u32 s1, s29, s1
	s_mul_i32 s9, s34, 0x3800
	s_mul_i32 s10, s34, 2
	s_mul_i32 s99, s9, 2
	s_mov_b32 s98, 0x3b800000
	v_mov_b32_e32 v178, 0x358637bd
	global_load_dwordx4 v[0:3], v66, s[20:21]
	global_load_dwordx4 v[4:7], v66, s[20:21] offset:16
	global_load_dwordx4 v[8:11], v66, s[20:21] offset:2048
	global_load_dwordx4 v[12:15], v66, s[20:21] offset:2064
	s_mov_b32 s6, s0
	s_mov_b32 s7, s1
	global_load_dwordx4 v[16:19], v65, s[6:7]
	global_load_dwordx4 v[20:23], v65, s[6:7] offset:1024
	global_load_dwordx4 v[24:27], v64, s[6:7]
	global_load_dwordx4 v[28:31], v64, s[6:7] offset:1024
	global_load_dword v67, v64, s[0:1]
	global_load_dword v67, v64, s[0:1] offset:1024
	s_add_u32 s6, s6, s9
	s_addc_u32 s7, s7, 0
	global_load_dwordx4 v[32:35], v65, s[6:7]
	global_load_dwordx4 v[36:39], v65, s[6:7] offset:1024
	global_load_dwordx4 v[40:43], v64, s[6:7]
	global_load_dwordx4 v[44:47], v64, s[6:7] offset:1024
	global_load_dword v67, v64, s[0:1]
	global_load_dword v67, v64, s[0:1] offset:1024
